# static raise of waves 0-3 in GEMM phases at priority level 3 instead of 1 (otherwise identical to v71)
# speedup vs baseline: 1.0089x; 1.0008x over previous
; __global__ void __launch_bounds__(NTHREADS, 2) mk_fwd(Args args) {
;     ...
;     if (IN(2)) { pg8::Gemm g{(const pg8::bf16_t*)WSB(WS_H), (const pg8::bf16_t*)WSB(WS_WAIN), NTOK, A_IN, DM, DM, DM};
;         pg8::StaticOrder S; S.init(NTOK, A_IN, G, bx); pg8::EpiAin E{(pg8::bf16_t*)WSB(WS_P), (pg8::bf16_t*)WSB(WS_VFIRST), WSF(WS_ROPE), (pg8::bf16_t*)WSB(WS_Y)};
;         pg8::gemm_phase<pg8::EpiAin, pg8::StaticOrder, true>(ldsb + RING_OFF, g, S, E); }
.LBB0_186:
	s_cmp_lt_i32 s58, 3
	s_cselect_b64 s[0:1], -1, 0
	s_cmp_gt_i32 s59, 2
	s_cselect_b64 s[2:3], -1, 0
	s_and_b64 s[10:11], s[0:1], s[2:3]
	s_andn2_b64 vcc, exec, s[10:11]
	s_cbranch_vccnz .LBB0_317
	v_readfirstlane_b32 s98, v0
	s_nop 3
	s_lshr_b32 s98, s98, 8
	s_cmp_eq_u32 s98, 0
	s_cbranch_scc0 .Lmy_prio0
	s_setprio 3

; #define KARG_DECL() const CAS char* ka_ = (const CAS char*)__builtin_amdgcn_kernarg_segment_ptr(); asm volatile("" : "+s"(ka_))
; #define GEMM_RESB(RF32, Ap, lda_, Btp, K_, Rp) do { pg8::Gemm g{(const pg8::bf16_t*)(Ap), (const pg8::bf16_t*)(Btp), NTOK, DM, (K_), (lda_), (K_)}; \
;         pg8::StaticOrder S; S.init(NTOK, DM, G, bx); pg8::EpiResB<RF32> E{(pg8::bf16_t*)WSB(WS_X), (const void*)(Rp)}; \
;         pg8::gemm_phase<pg8::EpiResB<RF32>, pg8::StaticOrder, true>(ldsb + RING_OFF, g, S, E); } while (0)
; __global__ void __launch_bounds__(NTHREADS, 2) mk_fwd(Args args) {
;     ...
;     if (IN(6)) { KARG_DECL(); GEMM_RESB(true, WSB(WS_CAT), A_CAT, WSB(WS_WAOUT), A_CAT, INF(0)); }
.LBB0_517:
	s_cmp_lt_i32 s58, 7
	s_cselect_b64 s[0:1], -1, 0
	s_cmp_gt_i32 s59, 6
	s_cselect_b64 s[2:3], -1, 0
	s_and_b64 s[4:5], s[0:1], s[2:3]
	s_andn2_b64 vcc, exec, s[4:5]
	s_cbranch_vccnz .LBB0_542
	v_readfirstlane_b32 s98, v0
	s_nop 3
	s_lshr_b32 s98, s98, 8
	s_cmp_eq_u32 s98, 0
	s_cbranch_scc0 .Lmy_prio1
	s_setprio 3

; #define KARG_DECL() const CAS char* ka_ = (const CAS char*)__builtin_amdgcn_kernarg_segment_ptr(); asm volatile("" : "+s"(ka_))
; #define GEMM_CONVACT(Ap, Btp, cwp, cbp) do { pg8::Gemm g{(const pg8::bf16_t*)(Ap), (const pg8::bf16_t*)(Btp), NTOK, DFF2, DM, DM, DM}; \
;         pg8::StaticOrder S; S.init(NTOK, DFF2, G, bx); pg8::EpiConvAct E{(pg8::bf16_t*)WSB(WS_ACT), WSF(WS_HALO), WSF(WS_RAWG), WSF(WS_RAWU), (cwp), (cbp)}; \
;         pg8::gemm_phase<pg8::EpiConvAct, pg8::StaticOrder, true>(ldsb + RING_OFF, g, S, E); } while (0)
; __global__ void __launch_bounds__(NTHREADS, 2) mk_fwd(Args args) {
;     ...
;     if (IN(8)) { KARG_DECL(); for (int rep_ = 0; rep_ < REP_UP; ++rep_) GEMM_CONVACT(WSB(WS_H), WSB(WS_WUP), INF(26), INF(27)); }
.LBB0_646:
	s_cmp_lt_i32 s58, 9
	s_cselect_b64 s[0:1], -1, 0
	s_and_b64 s[10:11], s[0:1], s[2:3]
	s_andn2_b64 vcc, exec, s[10:11]
	s_cbranch_vccnz .LBB0_675
	v_readfirstlane_b32 s98, v0
	s_nop 3
	s_lshr_b32 s98, s98, 8
	s_cmp_eq_u32 s98, 0
	s_cbranch_scc0 .Lmy_prio2
	s_setprio 3

; #define GEMM_RESB(RF32, Ap, lda_, Btp, K_, Rp) do { pg8::Gemm g{(const pg8::bf16_t*)(Ap), (const pg8::bf16_t*)(Btp), NTOK, DM, (K_), (lda_), (K_)}; \
;         pg8::StaticOrder S; S.init(NTOK, DM, G, bx); pg8::EpiResB<RF32> E{(pg8::bf16_t*)WSB(WS_X), (const void*)(Rp)}; \
;         pg8::gemm_phase<pg8::EpiResB<RF32>, pg8::StaticOrder, true>(ldsb + RING_OFF, g, S, E); } while (0)
; __global__ void __launch_bounds__(NTHREADS, 2) mk_fwd(Args args) {
;     ...
;     if (IN(10)) GEMM_RESB(false, WSB(WS_ACT), DFF, WSB(WS_WDOWN), DFF, WSB(WS_X));
.LBB0_790:
	s_cmp_lt_i32 s58, 11
	s_cselect_b64 s[0:1], -1, 0
	s_and_b64 s[6:7], s[0:1], s[2:3]
	s_andn2_b64 vcc, exec, s[6:7]
	s_cbranch_vccnz .LBB0_819
	v_readfirstlane_b32 s98, v0
	s_nop 3
	s_lshr_b32 s98, s98, 8
	s_cmp_eq_u32 s98, 0
	s_cbranch_scc0 .Lmy_prio3
	s_setprio 3

; #define GEMM_BF16(Ap, lda_, Btp, ldb_, M_, N_, K_, Op, ldc_) do { pg8::Gemm g{(const pg8::bf16_t*)(Ap), (const pg8::bf16_t*)(Btp), (M_), (N_), (K_), (lda_), (ldb_)}; \
;         pg8::StaticOrder S; S.init((M_), (N_), G, bx); pg8::EpiBf16P E{(pg8::bf16_t*)(Op), (ldc_)}; \
;         pg8::gemm_phase<pg8::EpiBf16P, pg8::StaticOrder, true>(ldsb + RING_OFF, g, S, E); } while (0)
; __global__ void __launch_bounds__(NTHREADS, 2) mk_fwd(Args args) {
;     ...
;     if (IN(12)) { GEMM_BF16(WSB(WS_H), DM, WSB(WS_WBIN), DM, NTOK, B_IN_PAD, DM, WSB(WS_P), LDP);
.LBB0_923:
	s_cmp_lt_i32 s58, 13
	s_cselect_b64 s[0:1], -1, 0
	s_and_b64 s[4:5], s[0:1], s[2:3]
	s_andn2_b64 vcc, exec, s[4:5]
	s_cbranch_vccnz .LBB0_951
	v_readfirstlane_b32 s98, v0
	s_nop 3
	s_lshr_b32 s98, s98, 8
	s_cmp_eq_u32 s98, 0
	s_cbranch_scc0 .Lmy_prio4
	s_setprio 3

; #define KARG_DECL() const CAS char* ka_ = (const CAS char*)__builtin_amdgcn_kernarg_segment_ptr(); asm volatile("" : "+s"(ka_))
; __global__ void __launch_bounds__(NTHREADS, 2) mk_fwd(Args args) {
;     ...
;     if (IN(14)) for (int rl_ = 0; rl_ < REP_LORA; ++rl_) { KARG_DECL();
.LBB0_1152:
	s_cmp_lt_i32 s58, 15
	s_cselect_b64 s[0:1], -1, 0
	s_and_b64 s[8:9], s[0:1], s[2:3]
	s_andn2_b64 vcc, exec, s[8:9]
	s_cbranch_vccnz .LBB0_1218
	v_readfirstlane_b32 s98, v0
	s_nop 3
	s_lshr_b32 s98, s98, 8
	s_cmp_eq_u32 s98, 0
	s_cbranch_scc0 .Lmy_prio5
	s_setprio 3

; #define GEMM_RESB(RF32, Ap, lda_, Btp, K_, Rp) do { pg8::Gemm g{(const pg8::bf16_t*)(Ap), (const pg8::bf16_t*)(Btp), NTOK, DM, (K_), (lda_), (K_)}; \
;         pg8::StaticOrder S; S.init(NTOK, DM, G, bx); pg8::EpiResB<RF32> E{(pg8::bf16_t*)WSB(WS_X), (const void*)(Rp)}; \
;         pg8::gemm_phase<pg8::EpiResB<RF32>, pg8::StaticOrder, true>(ldsb + RING_OFF, g, S, E); } while (0)
; __global__ void __launch_bounds__(NTHREADS, 2) mk_fwd(Args args) {
;     ...
;     if (IN(18)) GEMM_RESB(false, WSB(WS_CAT), DM, WSB(WS_WBOUT), DM, WSB(WS_X));
.LBB0_1405:
	s_cmp_lt_i32 s58, 19
	s_cselect_b64 s[0:1], -1, 0
	s_and_b64 s[4:5], s[0:1], s[4:5]
	s_andn2_b64 vcc, exec, s[4:5]
	s_cbranch_vccnz .LBB0_1430
	v_readfirstlane_b32 s98, v0
	s_nop 3
	s_lshr_b32 s98, s98, 8
	s_cmp_eq_u32 s98, 0
	s_cbranch_scc0 .Lmy_prio6
	s_setprio 3

; #define KARG_DECL() const CAS char* ka_ = (const CAS char*)__builtin_amdgcn_kernarg_segment_ptr(); asm volatile("" : "+s"(ka_))
; #define GEMM_CONVACT(Ap, Btp, cwp, cbp) do { pg8::Gemm g{(const pg8::bf16_t*)(Ap), (const pg8::bf16_t*)(Btp), NTOK, DFF2, DM, DM, DM}; \
;         pg8::StaticOrder S; S.init(NTOK, DFF2, G, bx); pg8::EpiConvAct E{(pg8::bf16_t*)WSB(WS_ACT), WSF(WS_HALO), WSF(WS_RAWG), WSF(WS_RAWU), (cwp), (cbp)}; \
;         pg8::gemm_phase<pg8::EpiConvAct, pg8::StaticOrder, true>(ldsb + RING_OFF, g, S, E); } while (0)
; __global__ void __launch_bounds__(NTHREADS, 2) mk_fwd(Args args) {
;     ...
;     if (IN(20)) { KARG_DECL(); for (int rep_ = 0; rep_ < REP_UP; ++rep_) GEMM_CONVACT(WSB(WS_H), WSB(WS_WUP) + WUP_L, INF(26) + 3 * DFF, INF(27) + DFF); }
.LBB0_1534:
	s_cmp_lt_i32 s58, 21
	s_cselect_b64 s[0:1], -1, 0
	s_and_b64 s[10:11], s[0:1], s[2:3]
	s_andn2_b64 vcc, exec, s[10:11]
	s_cbranch_vccnz .LBB0_1563
	v_readfirstlane_b32 s98, v0
	s_nop 3
	s_lshr_b32 s98, s98, 8
	s_cmp_eq_u32 s98, 0
	s_cbranch_scc0 .Lmy_prio7
	s_setprio 3

; #define GEMM_RESB(RF32, Ap, lda_, Btp, K_, Rp) do { pg8::Gemm g{(const pg8::bf16_t*)(Ap), (const pg8::bf16_t*)(Btp), NTOK, DM, (K_), (lda_), (K_)}; \
;         pg8::StaticOrder S; S.init(NTOK, DM, G, bx); pg8::EpiResB<RF32> E{(pg8::bf16_t*)WSB(WS_X), (const void*)(Rp)}; \
;         pg8::gemm_phase<pg8::EpiResB<RF32>, pg8::StaticOrder, true>(ldsb + RING_OFF, g, S, E); } while (0)
; __global__ void __launch_bounds__(NTHREADS, 2) mk_fwd(Args args) {
;     ...
;     if (IN(22)) GEMM_RESB(false, WSB(WS_ACT), DFF, WSB(WS_WDOWN) + WDOWN_L, DFF, WSB(WS_X));
.LBB0_1678:
	s_cmp_lt_i32 s58, 23
	s_cselect_b64 s[0:1], -1, 0
	s_and_b64 s[6:7], s[0:1], s[2:3]
	s_andn2_b64 vcc, exec, s[6:7]
	s_cbranch_vccnz .LBB0_1707
	v_readfirstlane_b32 s98, v0
	s_nop 3
	s_lshr_b32 s98, s98, 8
	s_cmp_eq_u32 s98, 0
	s_cbranch_scc0 .Lmy_prio8
	s_setprio 3
